# fused epilogue second row statistic: reductions of row groups 1-7 batched (2 LDS round trips instead of 14) before the atomic adds
# baseline (speedup 1.0000x reference)
.LBB0_603:
	s_or_b64 exec, exec, s[6:7]
	v_mul_f32_e32 v111, v111, v111
	v_mul_f32_e32 v107, v107, v107
	v_fmac_f32_e32 v111, v110, v110
	v_mul_f32_e32 v110, v113, v113
	v_fmac_f32_e32 v107, v106, v106
	v_mul_f32_e32 v106, v109, v109
	v_mul_f32_e32 v103, v103, v103
	v_fmac_f32_e32 v110, v112, v112
	v_fmac_f32_e32 v106, v108, v108
	v_fmac_f32_e32 v103, v102, v102
	v_mul_f32_e32 v102, v105, v105
	v_mul_f32_e32 v99, v99, v99
	v_add_f32_e32 v110, v111, v110
	v_add_f32_e32 v106, v107, v106
	v_fmac_f32_e32 v102, v104, v104
	v_fmac_f32_e32 v99, v98, v98
	v_mul_f32_e32 v98, v101, v101
	v_add_f32_e32 v106, v110, v106
	v_add_f32_e32 v102, v103, v102
	v_fmac_f32_e32 v98, v100, v100
	v_add_f32_e32 v102, v102, v106
	v_add_f32_e32 v98, v99, v98
	v_add_f32_e32 v98, v98, v102
	v_mul_f32_e32 v95, v95, v95
	v_mul_f32_e32 v91, v91, v91
	v_fmac_f32_e32 v95, v94, v94
	v_mul_f32_e32 v94, v97, v97
	v_fmac_f32_e32 v91, v90, v90
	v_mul_f32_e32 v90, v93, v93
	v_mul_f32_e32 v87, v87, v87
	v_fmac_f32_e32 v94, v96, v96
	v_fmac_f32_e32 v90, v92, v92
	v_fmac_f32_e32 v87, v86, v86
	v_mul_f32_e32 v86, v89, v89
	v_mul_f32_e32 v83, v83, v83
	v_add_f32_e32 v94, v95, v94
	v_add_f32_e32 v90, v91, v90
	v_fmac_f32_e32 v86, v88, v88
	v_fmac_f32_e32 v83, v82, v82
	v_mul_f32_e32 v82, v85, v85
	v_add_f32_e32 v90, v94, v90
	v_add_f32_e32 v86, v87, v86
	v_fmac_f32_e32 v82, v84, v84
	v_add_f32_e32 v86, v86, v90
	v_add_f32_e32 v82, v83, v82
	v_add_f32_e32 v82, v82, v86
	v_mul_f32_e32 v79, v79, v79
	v_mul_f32_e32 v75, v75, v75
	v_fmac_f32_e32 v79, v78, v78
	v_mul_f32_e32 v78, v81, v81
	v_fmac_f32_e32 v75, v74, v74
	v_mul_f32_e32 v74, v77, v77
	v_mul_f32_e32 v71, v71, v71
	v_fmac_f32_e32 v78, v80, v80
	v_fmac_f32_e32 v74, v76, v76
	v_fmac_f32_e32 v71, v70, v70
	v_mul_f32_e32 v70, v73, v73
	v_mul_f32_e32 v67, v67, v67
	v_add_f32_e32 v78, v79, v78
	v_add_f32_e32 v74, v75, v74
	v_fmac_f32_e32 v70, v72, v72
	v_fmac_f32_e32 v67, v66, v66
	v_mul_f32_e32 v66, v69, v69
	v_add_f32_e32 v74, v78, v74
	v_add_f32_e32 v70, v71, v70
	v_fmac_f32_e32 v66, v68, v68
	v_add_f32_e32 v70, v70, v74
	v_add_f32_e32 v66, v67, v66
	v_add_f32_e32 v66, v66, v70
	v_mul_f32_e32 v63, v63, v63
	v_mul_f32_e32 v59, v59, v59
	v_fmac_f32_e32 v63, v62, v62
	v_mul_f32_e32 v62, v65, v65
	v_fmac_f32_e32 v59, v58, v58
	v_mul_f32_e32 v58, v61, v61
	v_mul_f32_e32 v55, v55, v55
	v_fmac_f32_e32 v62, v64, v64
	v_fmac_f32_e32 v58, v60, v60
	v_fmac_f32_e32 v55, v54, v54
	v_mul_f32_e32 v54, v57, v57
	v_mul_f32_e32 v51, v51, v51
	v_add_f32_e32 v62, v63, v62
	v_add_f32_e32 v58, v59, v58
	v_fmac_f32_e32 v54, v56, v56
	v_fmac_f32_e32 v51, v50, v50
	v_mul_f32_e32 v50, v53, v53
	v_add_f32_e32 v58, v62, v58
	v_add_f32_e32 v54, v55, v54
	v_fmac_f32_e32 v50, v52, v52
	v_add_f32_e32 v54, v54, v58
	v_add_f32_e32 v50, v51, v50
	v_add_f32_e32 v50, v50, v54
	v_mul_f32_e32 v47, v47, v47
	v_mul_f32_e32 v43, v43, v43
	v_fmac_f32_e32 v47, v46, v46
	v_mul_f32_e32 v46, v49, v49
	v_fmac_f32_e32 v43, v42, v42
	v_mul_f32_e32 v42, v45, v45
	v_mul_f32_e32 v39, v39, v39
	v_fmac_f32_e32 v46, v48, v48
	v_fmac_f32_e32 v42, v44, v44
	v_fmac_f32_e32 v39, v38, v38
	v_mul_f32_e32 v38, v41, v41
	v_mul_f32_e32 v35, v35, v35
	v_add_f32_e32 v46, v47, v46
	v_add_f32_e32 v42, v43, v42
	v_fmac_f32_e32 v38, v40, v40
	v_fmac_f32_e32 v35, v34, v34
	v_mul_f32_e32 v34, v37, v37
	v_add_f32_e32 v42, v46, v42
	v_add_f32_e32 v38, v39, v38
	v_fmac_f32_e32 v34, v36, v36
	v_add_f32_e32 v38, v38, v42
	v_add_f32_e32 v34, v35, v34
	v_add_f32_e32 v34, v34, v38
	v_mul_f32_e32 v31, v31, v31
	v_mul_f32_e32 v27, v27, v27
	v_fmac_f32_e32 v31, v30, v30
	v_mul_f32_e32 v30, v33, v33
	v_fmac_f32_e32 v27, v26, v26
	v_mul_f32_e32 v26, v29, v29
	v_mul_f32_e32 v23, v23, v23
	v_fmac_f32_e32 v30, v32, v32
	v_fmac_f32_e32 v26, v28, v28
	v_fmac_f32_e32 v23, v22, v22
	v_mul_f32_e32 v22, v25, v25
	v_mul_f32_e32 v19, v19, v19
	v_add_f32_e32 v30, v31, v30
	v_add_f32_e32 v26, v27, v26
	v_fmac_f32_e32 v22, v24, v24
	v_fmac_f32_e32 v19, v18, v18
	v_mul_f32_e32 v18, v21, v21
	v_add_f32_e32 v26, v30, v26
	v_add_f32_e32 v22, v23, v22
	v_fmac_f32_e32 v18, v20, v20
	v_add_f32_e32 v22, v22, v26
	v_add_f32_e32 v18, v19, v18
	v_add_f32_e32 v18, v18, v22
	v_mul_f32_e32 v15, v15, v15
	v_mul_f32_e32 v11, v11, v11
	v_fmac_f32_e32 v15, v14, v14
	v_mul_f32_e32 v14, v17, v17
	v_fmac_f32_e32 v11, v10, v10
	v_mul_f32_e32 v10, v13, v13
	v_mul_f32_e32 v7, v7, v7
	v_fmac_f32_e32 v14, v16, v16
	v_fmac_f32_e32 v10, v12, v12
	v_fmac_f32_e32 v7, v6, v6
	v_mul_f32_e32 v6, v9, v9
	v_mul_f32_e32 v3, v3, v3
	v_add_f32_e32 v14, v15, v14
	v_add_f32_e32 v10, v11, v10
	v_fmac_f32_e32 v6, v8, v8
	v_fmac_f32_e32 v3, v2, v2
	v_mul_f32_e32 v2, v5, v5
	v_add_f32_e32 v10, v14, v10
	v_add_f32_e32 v6, v7, v6
	v_fmac_f32_e32 v2, v4, v4
	v_add_f32_e32 v6, v6, v10
	v_add_f32_e32 v2, v3, v2
	v_add_f32_e32 v2, v2, v6
	ds_bpermute_b32 v99, v236, v98
	ds_bpermute_b32 v83, v236, v82
	ds_bpermute_b32 v67, v236, v66
	ds_bpermute_b32 v51, v236, v50
	ds_bpermute_b32 v35, v236, v34
	ds_bpermute_b32 v19, v236, v18
	ds_bpermute_b32 v3, v236, v2
	s_waitcnt lgkmcnt(0)
	v_add_f32_e32 v98, v98, v99
	v_add_f32_e32 v82, v82, v83
	v_add_f32_e32 v66, v66, v67
	v_add_f32_e32 v50, v50, v51
	v_add_f32_e32 v34, v34, v35
	v_add_f32_e32 v18, v18, v19
	v_add_f32_e32 v2, v2, v3
	ds_bpermute_b32 v99, v237, v98
	ds_bpermute_b32 v83, v237, v82
	ds_bpermute_b32 v67, v237, v66
	ds_bpermute_b32 v51, v237, v50
	ds_bpermute_b32 v35, v237, v34
	ds_bpermute_b32 v19, v237, v18
	ds_bpermute_b32 v3, v237, v2
	s_waitcnt lgkmcnt(0)
	s_and_saveexec_b64 s[6:7], s[4:5]
	v_add_f32_e32 v98, v98, v99
	v_min_f32_e32 v98, 0x49742400, v98
	v_fma_f32 v98, v98, s18, 0.5
	v_cvt_u32_f32_e32 v98, v98
	v_add_f32_e32 v82, v82, v83
	v_min_f32_e32 v82, 0x49742400, v82
	v_fma_f32 v82, v82, s18, 0.5
	v_cvt_u32_f32_e32 v82, v82
	v_add_f32_e32 v66, v66, v67
	v_min_f32_e32 v66, 0x49742400, v66
	v_fma_f32 v66, v66, s18, 0.5
	v_cvt_u32_f32_e32 v66, v66
	v_add_f32_e32 v50, v50, v51
	v_min_f32_e32 v50, 0x49742400, v50
	v_fma_f32 v50, v50, s18, 0.5
	v_cvt_u32_f32_e32 v50, v50
	v_add_f32_e32 v34, v34, v35
	v_min_f32_e32 v34, 0x49742400, v34
	v_fma_f32 v34, v34, s18, 0.5
	v_cvt_u32_f32_e32 v34, v34
	v_add_f32_e32 v18, v18, v19
	v_min_f32_e32 v18, 0x49742400, v18
	v_fma_f32 v18, v18, s18, 0.5
	v_cvt_u32_f32_e32 v18, v18
	v_add_f32_e32 v2, v2, v3
	v_min_f32_e32 v2, 0x49742400, v2
	v_fma_f32 v2, v2, s18, 0.5
	v_cvt_u32_f32_e32 v2, v2
	s_lshl_b64 s[14:15], s[8:9], 2
	s_add_u32 s16, s11, s14
	s_addc_u32 s17, s10, s15
	s_lshl_b64 s[14:15], s[12:13], 2
	s_add_u32 s14, s16, s14
	s_addc_u32 s15, s17, s15
	global_atomic_add v1, v98, s[14:15] offset:64
	global_atomic_add v1, v82, s[14:15] offset:128
	global_atomic_add v1, v66, s[14:15] offset:192
	global_atomic_add v1, v50, s[14:15] offset:512
	global_atomic_add v1, v34, s[14:15] offset:576
	global_atomic_add v1, v18, s[14:15] offset:640
	s_lshl_b64 s[4:5], s[8:9], 2
	s_add_u32 s8, s11, s4
	s_addc_u32 s9, s10, s5
	s_lshl_b64 s[4:5], s[12:13], 2
	s_add_u32 s4, s8, s4
	s_addc_u32 s5, s9, s5
	global_atomic_add v1, v2, s[4:5] offset:704
	s_or_b64 exec, exec, s[6:7]
